# norm2 touches the workgroup's first up-projection weight tiles (one line per lane) so they are L2-resident at the start of the up phase
# baseline (speedup 1.0000x reference)
.LBB0_82:
	v_readlane_b32 s34, v239, 29
	v_readlane_b32 s35, v239, 30
	s_and_b64 vcc, exec, s[4:5]
	s_cbranch_vccz .LBB0_99
	s_waitcnt lgkmcnt(0)
	s_lshl_b32 s7, s79, 12
	s_add_u32 s18, s18, s7
	s_addc_u32 s19, s19, 0
	v_readlane_b32 s14, v239, 51
	v_readlane_b32 s15, v239, 52
	v_and_b32_e32 v8, 63, v211
	v_lshlrev_b32_e32 v0, 5, v8
	v_lshlrev_b32_e32 v1, 4, v8
	v_lshlrev_b32_e32 v9, 2, v8
	v_xor_b32_e32 v2, 0x4, v9
	v_xor_b32_e32 v3, 0x8, v9
	v_xor_b32_e32 v4, 0x10, v9
	v_xor_b32_e32 v5, 0x20, v9
	v_xor_b32_e32 v6, 0x40, v9
	v_xor_b32_e32 v7, 0x80, v9
	v_readlane_b32 s3, v240, 55
	v_readlane_b32 s6, v239, 10
	s_lshr_b32 s3, s3, 6
	s_lshl_b32 s3, s3, 2
	s_and_b32 s7, s78, 7
	s_lshl_b32 s7, s7, 10
	s_add_i32 s3, s3, s7
	s_bfe_u32 s7, s78, 0x20003
	s_lshl_b32 s7, s7, 8
	s_add_i32 s3, s3, s7
	s_lshr_b32 s7, s78, 5
	s_lshl_b32 s7, s7, 5
	s_add_i32 s3, s3, s7
	s_lshl_b32 s6, s6, 3
	v_readlane_b32 s12, v240, 55
	s_lshr_b32 s13, s78, 5
	s_lshl_b32 s13, s13, 19
	s_lshr_b32 s12, s12, 6
	s_lshl_b32 s12, s12, 16
	s_add_i32 s12, s12, s13
	s_mul_i32 s13, s79, 0xb00000
	s_add_i32 s12, s12, s13
	s_add_i32 s12, s12, 0x2700000
	v_lshrrev_b32_e32 v166, 1, v8
	v_lshlrev_b32_e32 v166, 11, v166
	v_and_b32_e32 v167, 1, v8
	v_lshl_add_u32 v166, v167, 7, v166
	v_add_u32_e32 v166, s12, v166
	s_cmpk_lt_i32 s3, 0x2000
	s_cbranch_scc0 .Lnorm2_end
.Lnorm2_loop:
	s_mov_b32 s8, s3
	s_add_i32 s9, s8, 1
	s_add_i32 s10, s9, 1
	s_add_i32 s11, s10, 1
	s_cmpk_lt_i32 s9, 0x2000
	s_cselect_b32 s9, s9, s3
	s_cmpk_lt_i32 s10, 0x2000
	s_cselect_b32 s10, s10, s3
	s_cmpk_lt_i32 s11, 0x2000
	s_cselect_b32 s11, s11, s3
	s_lshl_b32 s7, s8, 12
	s_add_u32 s4, s34, s7
	s_addc_u32 s5, s35, 0
	s_add_u32 s4, s4, 0x6900000
	s_addc_u32 s5, s5, 0
	global_load_dwordx4 v[16:19], v0, s[4:5]
	global_load_dwordx4 v[20:23], v0, s[4:5] offset:16
	global_load_dwordx4 v[24:27], v0, s[4:5] offset:2048
	global_load_dwordx4 v[28:31], v0, s[4:5] offset:2064
	s_lshl_b32 s7, s9, 12
	s_add_u32 s4, s34, s7
	s_addc_u32 s5, s35, 0
	s_add_u32 s4, s4, 0x6900000
	s_addc_u32 s5, s5, 0
	global_load_dwordx4 v[32:35], v0, s[4:5]
	global_load_dwordx4 v[36:39], v0, s[4:5] offset:16
	global_load_dwordx4 v[40:43], v0, s[4:5] offset:2048
	global_load_dwordx4 v[44:47], v0, s[4:5] offset:2064
	s_lshl_b32 s7, s10, 12
	s_add_u32 s4, s34, s7
	s_addc_u32 s5, s35, 0
	s_add_u32 s4, s4, 0x6900000
	s_addc_u32 s5, s5, 0
	global_load_dwordx4 v[48:51], v0, s[4:5]
	global_load_dwordx4 v[52:55], v0, s[4:5] offset:16
	global_load_dwordx4 v[56:59], v0, s[4:5] offset:2048
	global_load_dwordx4 v[60:63], v0, s[4:5] offset:2064
	s_lshl_b32 s7, s11, 12
	s_add_u32 s4, s34, s7
	s_addc_u32 s5, s35, 0
	s_add_u32 s4, s4, 0x6900000
	s_addc_u32 s5, s5, 0
	global_load_dwordx4 v[64:67], v0, s[4:5]
	global_load_dwordx4 v[68:71], v0, s[4:5] offset:16
	global_load_dwordx4 v[72:75], v0, s[4:5] offset:2048
	global_load_dwordx4 v[76:79], v0, s[4:5] offset:2064
	global_load_dwordx4 v[80:83], v0, s[18:19]
	global_load_dwordx4 v[84:87], v0, s[18:19] offset:16
	global_load_dwordx4 v[88:91], v0, s[18:19] offset:2048
	global_load_dwordx4 v[92:95], v0, s[18:19] offset:2064
	s_sub_i32 s7, s8, 0x1000
	s_lshr_b32 s7, s7, 11
	s_add_i32 s7, s7, 1
	s_cmpk_lt_i32 s8, 0x1000
	s_cselect_b32 s7, 0, s7
	s_mulk_i32 s7, 0x6000
	s_add_i32 s7, s7, 0x3000
	s_add_u32 s4, s14, s7
	s_addc_u32 s5, s15, 0
	global_load_dwordx4 v[112:115], v0, s[4:5]
	global_load_dwordx4 v[116:119], v0, s[4:5] offset:16
	global_load_dwordx4 v[120:123], v0, s[4:5] offset:2048
	global_load_dwordx4 v[124:127], v0, s[4:5] offset:2064
	s_add_u32 s4, s4, 0x1000
	s_addc_u32 s5, s5, 0
	global_load_dwordx4 v[96:99], v0, s[4:5]
	global_load_dwordx4 v[100:103], v0, s[4:5] offset:16
	global_load_dwordx4 v[104:107], v0, s[4:5] offset:2048
	global_load_dwordx4 v[108:111], v0, s[4:5] offset:2064
	s_sub_i32 s7, s9, 0x1000
	s_lshr_b32 s7, s7, 11
	s_add_i32 s7, s7, 1
	s_cmpk_lt_i32 s9, 0x1000
	s_cselect_b32 s7, 0, s7
	s_mulk_i32 s7, 0x6000
	s_add_i32 s7, s7, 0x3000
	s_add_u32 s4, s14, s7
	s_addc_u32 s5, s15, 0
	global_load_dwordx4 v[144:147], v0, s[4:5]
	global_load_dwordx4 v[148:151], v0, s[4:5] offset:16
	global_load_dwordx4 v[152:155], v0, s[4:5] offset:2048
	global_load_dwordx4 v[156:159], v0, s[4:5] offset:2064
	s_add_u32 s4, s4, 0x1000
	s_addc_u32 s5, s5, 0
	global_load_dwordx4 v[128:131], v0, s[4:5]
	global_load_dwordx4 v[132:135], v0, s[4:5] offset:16
	global_load_dwordx4 v[136:139], v0, s[4:5] offset:2048
	global_load_dwordx4 v[140:143], v0, s[4:5] offset:2064
	global_load_dword v167, v166, s[34:35]
	s_waitcnt vmcnt(33)
	v_mul_f32_e32 v160, v17, v17
	v_mul_f32_e32 v9, v19, v19
	v_fmac_f32_e32 v160, v16, v16
	v_fmac_f32_e32 v9, v18, v18
	v_add_f32_e32 v160, v160, v9
	v_mul_f32_e32 v8, v21, v21
	v_mul_f32_e32 v9, v23, v23
	v_fmac_f32_e32 v8, v20, v20
	v_fmac_f32_e32 v9, v22, v22
	v_add_f32_e32 v8, v8, v9
	v_add_f32_e32 v160, v160, v8
	v_mul_f32_e32 v8, v25, v25
	v_mul_f32_e32 v9, v27, v27
	v_fmac_f32_e32 v8, v24, v24
	v_fmac_f32_e32 v9, v26, v26
	v_add_f32_e32 v8, v8, v9
	v_add_f32_e32 v160, v160, v8
	v_mul_f32_e32 v8, v29, v29
	v_mul_f32_e32 v9, v31, v31
	v_fmac_f32_e32 v8, v28, v28
	v_fmac_f32_e32 v9, v30, v30
	v_add_f32_e32 v8, v8, v9
	v_add_f32_e32 v160, v160, v8
	s_waitcnt vmcnt(29)
	v_mul_f32_e32 v161, v33, v33
	v_mul_f32_e32 v9, v35, v35
	v_fmac_f32_e32 v161, v32, v32
	v_fmac_f32_e32 v9, v34, v34
	v_add_f32_e32 v161, v161, v9
	v_mul_f32_e32 v8, v37, v37
	v_mul_f32_e32 v9, v39, v39
	v_fmac_f32_e32 v8, v36, v36
	v_fmac_f32_e32 v9, v38, v38
	v_add_f32_e32 v8, v8, v9
	v_add_f32_e32 v161, v161, v8
	v_mul_f32_e32 v8, v41, v41
	v_mul_f32_e32 v9, v43, v43
	v_fmac_f32_e32 v8, v40, v40
	v_fmac_f32_e32 v9, v42, v42
	v_add_f32_e32 v8, v8, v9
	v_add_f32_e32 v161, v161, v8
	v_mul_f32_e32 v8, v45, v45
	v_mul_f32_e32 v9, v47, v47
	v_fmac_f32_e32 v8, v44, v44
	v_fmac_f32_e32 v9, v46, v46
	v_add_f32_e32 v8, v8, v9
	v_add_f32_e32 v161, v161, v8
	s_waitcnt vmcnt(25)
	v_mul_f32_e32 v162, v49, v49
	v_mul_f32_e32 v9, v51, v51
	v_fmac_f32_e32 v162, v48, v48
	v_fmac_f32_e32 v9, v50, v50
	v_add_f32_e32 v162, v162, v9
	v_mul_f32_e32 v8, v53, v53
	v_mul_f32_e32 v9, v55, v55
	v_fmac_f32_e32 v8, v52, v52
	v_fmac_f32_e32 v9, v54, v54
	v_add_f32_e32 v8, v8, v9
	v_add_f32_e32 v162, v162, v8
	v_mul_f32_e32 v8, v57, v57
	v_mul_f32_e32 v9, v59, v59
	v_fmac_f32_e32 v8, v56, v56
	v_fmac_f32_e32 v9, v58, v58
	v_add_f32_e32 v8, v8, v9
	v_add_f32_e32 v162, v162, v8
	v_mul_f32_e32 v8, v61, v61
	v_mul_f32_e32 v9, v63, v63
	v_fmac_f32_e32 v8, v60, v60
	v_fmac_f32_e32 v9, v62, v62
	v_add_f32_e32 v8, v8, v9
	v_add_f32_e32 v162, v162, v8
	s_waitcnt vmcnt(21)
	v_mul_f32_e32 v163, v65, v65
	v_mul_f32_e32 v9, v67, v67
	v_fmac_f32_e32 v163, v64, v64
	v_fmac_f32_e32 v9, v66, v66
	v_add_f32_e32 v163, v163, v9
	v_mul_f32_e32 v8, v69, v69
	v_mul_f32_e32 v9, v71, v71
	v_fmac_f32_e32 v8, v68, v68
	v_fmac_f32_e32 v9, v70, v70
	v_add_f32_e32 v8, v8, v9
	v_add_f32_e32 v163, v163, v8
	v_mul_f32_e32 v8, v73, v73
	v_mul_f32_e32 v9, v75, v75
	v_fmac_f32_e32 v8, v72, v72
	v_fmac_f32_e32 v9, v74, v74
	v_add_f32_e32 v8, v8, v9
	v_add_f32_e32 v163, v163, v8
	v_mul_f32_e32 v8, v77, v77
	v_mul_f32_e32 v9, v79, v79
	v_fmac_f32_e32 v8, v76, v76
	v_fmac_f32_e32 v9, v78, v78
	v_add_f32_e32 v8, v8, v9
	v_add_f32_e32 v163, v163, v8
	ds_bpermute_b32 v8, v2, v160
	ds_bpermute_b32 v9, v2, v161
	ds_bpermute_b32 v10, v2, v162
	ds_bpermute_b32 v11, v2, v163
	s_waitcnt lgkmcnt(3)
	v_add_f32_e32 v160, v160, v8
	s_waitcnt lgkmcnt(2)
	v_add_f32_e32 v161, v161, v9
	s_waitcnt lgkmcnt(1)
	v_add_f32_e32 v162, v162, v10
	s_waitcnt lgkmcnt(0)
	v_add_f32_e32 v163, v163, v11
	ds_bpermute_b32 v8, v3, v160
	ds_bpermute_b32 v9, v3, v161
	ds_bpermute_b32 v10, v3, v162
	ds_bpermute_b32 v11, v3, v163
	s_waitcnt lgkmcnt(3)
	v_add_f32_e32 v160, v160, v8
	s_waitcnt lgkmcnt(2)
	v_add_f32_e32 v161, v161, v9
	s_waitcnt lgkmcnt(1)
	v_add_f32_e32 v162, v162, v10
	s_waitcnt lgkmcnt(0)
	v_add_f32_e32 v163, v163, v11
	ds_bpermute_b32 v8, v4, v160
	ds_bpermute_b32 v9, v4, v161
	ds_bpermute_b32 v10, v4, v162
	ds_bpermute_b32 v11, v4, v163
	s_waitcnt lgkmcnt(3)
	v_add_f32_e32 v160, v160, v8
	s_waitcnt lgkmcnt(2)
	v_add_f32_e32 v161, v161, v9
	s_waitcnt lgkmcnt(1)
	v_add_f32_e32 v162, v162, v10
	s_waitcnt lgkmcnt(0)
	v_add_f32_e32 v163, v163, v11
	ds_bpermute_b32 v8, v5, v160
	ds_bpermute_b32 v9, v5, v161
	ds_bpermute_b32 v10, v5, v162
	ds_bpermute_b32 v11, v5, v163
	s_waitcnt lgkmcnt(3)
	v_add_f32_e32 v160, v160, v8
	s_waitcnt lgkmcnt(2)
	v_add_f32_e32 v161, v161, v9
	s_waitcnt lgkmcnt(1)
	v_add_f32_e32 v162, v162, v10
	s_waitcnt lgkmcnt(0)
	v_add_f32_e32 v163, v163, v11
	ds_bpermute_b32 v8, v6, v160
	ds_bpermute_b32 v9, v6, v161
	ds_bpermute_b32 v10, v6, v162
	ds_bpermute_b32 v11, v6, v163
	s_waitcnt lgkmcnt(3)
	v_add_f32_e32 v160, v160, v8
	s_waitcnt lgkmcnt(2)
	v_add_f32_e32 v161, v161, v9
	s_waitcnt lgkmcnt(1)
	v_add_f32_e32 v162, v162, v10
	s_waitcnt lgkmcnt(0)
	v_add_f32_e32 v163, v163, v11
	ds_bpermute_b32 v8, v7, v160
	ds_bpermute_b32 v9, v7, v161
	ds_bpermute_b32 v10, v7, v162
	ds_bpermute_b32 v11, v7, v163
	s_waitcnt lgkmcnt(3)
	v_add_f32_e32 v160, v160, v8
	s_waitcnt lgkmcnt(2)
	v_add_f32_e32 v161, v161, v9
	s_waitcnt lgkmcnt(1)
	v_add_f32_e32 v162, v162, v10
	s_waitcnt lgkmcnt(0)
	v_add_f32_e32 v163, v163, v11
	s_mov_b32 s7, 0xf800000
	v_fmamk_f32 v160, v160, 0x3a800000, v190
	v_mul_f32_e32 v8, 0x4f800000, v160
	v_cmp_gt_f32_e32 vcc, s7, v160
	s_nop 1
	v_cndmask_b32_e32 v160, v160, v8, vcc
	v_sqrt_f32_e32 v8, v160
	s_nop 0
	v_add_u32_e32 v9, -1, v8
	v_fma_f32 v10, -v9, v8, v160
	v_cmp_ge_f32_e64 s[4:5], 0, v10
	v_add_u32_e32 v10, 1, v8
	s_nop 0
	v_cndmask_b32_e64 v9, v8, v9, s[4:5]
	v_fma_f32 v8, -v10, v8, v160
	v_cmp_lt_f32_e64 s[4:5], 0, v8
	s_nop 1
	v_cndmask_b32_e64 v8, v9, v10, s[4:5]
	v_mul_f32_e32 v9, 0x37800000, v8
	v_cndmask_b32_e32 v8, v8, v9, vcc
	v_cmp_class_f32_e32 vcc, v160, v191
	s_nop 1
	v_cndmask_b32_e32 v160, v8, v160, vcc
	v_div_scale_f32 v8, s[4:5], v160, v160, 1.0
	v_rcp_f32_e32 v9, v8
	s_nop 0
	v_fma_f32 v10, -v8, v9, 1.0
	v_fmac_f32_e32 v9, v10, v9
	v_div_scale_f32 v10, vcc, 1.0, v160, 1.0
	v_mul_f32_e32 v11, v10, v9
	v_fma_f32 v12, -v8, v11, v10
	v_fmac_f32_e32 v11, v12, v9
	v_fma_f32 v8, -v8, v11, v10
	v_div_fmas_f32 v8, v8, v9, v11
	v_div_fixup_f32 v160, v8, v160, 1.0
	s_mov_b32 s7, 0xf800000
	v_fmamk_f32 v161, v161, 0x3a800000, v190
	v_mul_f32_e32 v8, 0x4f800000, v161
	v_cmp_gt_f32_e32 vcc, s7, v161
	s_nop 1
	v_cndmask_b32_e32 v161, v161, v8, vcc
	v_sqrt_f32_e32 v8, v161
	s_nop 0
	v_add_u32_e32 v9, -1, v8
	v_fma_f32 v10, -v9, v8, v161
	v_cmp_ge_f32_e64 s[4:5], 0, v10
	v_add_u32_e32 v10, 1, v8
	s_nop 0
	v_cndmask_b32_e64 v9, v8, v9, s[4:5]
	v_fma_f32 v8, -v10, v8, v161
	v_cmp_lt_f32_e64 s[4:5], 0, v8
	s_nop 1
	v_cndmask_b32_e64 v8, v9, v10, s[4:5]
	v_mul_f32_e32 v9, 0x37800000, v8
	v_cndmask_b32_e32 v8, v8, v9, vcc
	v_cmp_class_f32_e32 vcc, v161, v191
	s_nop 1
	v_cndmask_b32_e32 v161, v8, v161, vcc
	v_div_scale_f32 v8, s[4:5], v161, v161, 1.0
	v_rcp_f32_e32 v9, v8
	s_nop 0
	v_fma_f32 v10, -v8, v9, 1.0
	v_fmac_f32_e32 v9, v10, v9
	v_div_scale_f32 v10, vcc, 1.0, v161, 1.0
	v_mul_f32_e32 v11, v10, v9
	v_fma_f32 v12, -v8, v11, v10
	v_fmac_f32_e32 v11, v12, v9
	v_fma_f32 v8, -v8, v11, v10
	v_div_fmas_f32 v8, v8, v9, v11
	v_div_fixup_f32 v161, v8, v161, 1.0
	s_mov_b32 s7, 0xf800000
	v_fmamk_f32 v162, v162, 0x3a800000, v190
	v_mul_f32_e32 v8, 0x4f800000, v162
	v_cmp_gt_f32_e32 vcc, s7, v162
	s_nop 1
	v_cndmask_b32_e32 v162, v162, v8, vcc
	v_sqrt_f32_e32 v8, v162
	s_nop 0
	v_add_u32_e32 v9, -1, v8
	v_fma_f32 v10, -v9, v8, v162
	v_cmp_ge_f32_e64 s[4:5], 0, v10
	v_add_u32_e32 v10, 1, v8
	s_nop 0
	v_cndmask_b32_e64 v9, v8, v9, s[4:5]
	v_fma_f32 v8, -v10, v8, v162
	v_cmp_lt_f32_e64 s[4:5], 0, v8
	s_nop 1
	v_cndmask_b32_e64 v8, v9, v10, s[4:5]
	v_mul_f32_e32 v9, 0x37800000, v8
	v_cndmask_b32_e32 v8, v8, v9, vcc
	v_cmp_class_f32_e32 vcc, v162, v191
	s_nop 1
	v_cndmask_b32_e32 v162, v8, v162, vcc
	v_div_scale_f32 v8, s[4:5], v162, v162, 1.0
	v_rcp_f32_e32 v9, v8
	s_nop 0
	v_fma_f32 v10, -v8, v9, 1.0
	v_fmac_f32_e32 v9, v10, v9
	v_div_scale_f32 v10, vcc, 1.0, v162, 1.0
	v_mul_f32_e32 v11, v10, v9
	v_fma_f32 v12, -v8, v11, v10
	v_fmac_f32_e32 v11, v12, v9
	v_fma_f32 v8, -v8, v11, v10
	v_div_fmas_f32 v8, v8, v9, v11
	v_div_fixup_f32 v162, v8, v162, 1.0
	s_mov_b32 s7, 0xf800000
	v_fmamk_f32 v163, v163, 0x3a800000, v190
	v_mul_f32_e32 v8, 0x4f800000, v163
	v_cmp_gt_f32_e32 vcc, s7, v163
	s_nop 1
	v_cndmask_b32_e32 v163, v163, v8, vcc
	v_sqrt_f32_e32 v8, v163
	s_nop 0
	v_add_u32_e32 v9, -1, v8
	v_fma_f32 v10, -v9, v8, v163
	v_cmp_ge_f32_e64 s[4:5], 0, v10
	v_add_u32_e32 v10, 1, v8
	s_nop 0
	v_cndmask_b32_e64 v9, v8, v9, s[4:5]
	v_fma_f32 v8, -v10, v8, v163
	v_cmp_lt_f32_e64 s[4:5], 0, v8
	s_nop 1
	v_cndmask_b32_e64 v8, v9, v10, s[4:5]
	v_mul_f32_e32 v9, 0x37800000, v8
	v_cndmask_b32_e32 v8, v8, v9, vcc
	v_cmp_class_f32_e32 vcc, v163, v191
	s_nop 1
	v_cndmask_b32_e32 v163, v8, v163, vcc
	v_div_scale_f32 v8, s[4:5], v163, v163, 1.0
	v_rcp_f32_e32 v9, v8
	s_nop 0
	v_fma_f32 v10, -v8, v9, 1.0
	v_fmac_f32_e32 v9, v10, v9
	v_div_scale_f32 v10, vcc, 1.0, v163, 1.0
	v_mul_f32_e32 v11, v10, v9
	v_fma_f32 v12, -v8, v11, v10
	v_fmac_f32_e32 v11, v12, v9
	v_fma_f32 v8, -v8, v11, v10
	v_div_fmas_f32 v8, v8, v9, v11
	v_div_fixup_f32 v163, v8, v163, 1.0
	s_waitcnt vmcnt(8)
	s_lshl_b32 s7, s8, 11
	s_add_u32 s4, s34, s7
	s_addc_u32 s5, s35, 0
	s_add_u32 s4, s4, 0x8900000
	s_addc_u32 s5, s5, 0
	v_mul_f32_e32 v19, v19, v160
	v_mul_f32_e32 v19, v83, v19
	v_mul_f32_e32 v18, v18, v160
	v_mul_f32_e32 v18, v82, v18
	v_mul_f32_e32 v17, v17, v160
	v_mul_f32_e32 v17, v81, v17
	v_mul_f32_e32 v16, v16, v160
	v_mul_f32_e32 v16, v80, v16
	v_add_f32_e32 v11, 1.0, v99
	v_fma_f32 v19, v11, v19, v115
	v_add_f32_e32 v10, 1.0, v98
	v_fma_f32 v18, v10, v18, v114
	v_add_f32_e32 v9, 1.0, v97
	v_fma_f32 v17, v9, v17, v113
	v_add_f32_e32 v8, 1.0, v96
	v_fma_f32 v16, v8, v16, v112
	v_mul_f32_e32 v23, v23, v160
	v_mul_f32_e32 v23, v87, v23
	v_mul_f32_e32 v22, v22, v160
	v_mul_f32_e32 v22, v86, v22
	v_mul_f32_e32 v21, v21, v160
	v_mul_f32_e32 v21, v85, v21
	v_mul_f32_e32 v20, v20, v160
	v_mul_f32_e32 v20, v84, v20
	v_add_f32_e32 v11, 1.0, v103
	v_fma_f32 v23, v11, v23, v119
	v_add_f32_e32 v10, 1.0, v102
	v_fma_f32 v22, v10, v22, v118
	v_add_f32_e32 v9, 1.0, v101
	v_fma_f32 v21, v9, v21, v117
	v_add_f32_e32 v8, 1.0, v100
	v_fma_f32 v20, v8, v20, v116
	v_cvt_pk_bf16_f32 v16, v16, v17
	v_cvt_pk_bf16_f32 v17, v18, v19
	v_cvt_pk_bf16_f32 v18, v20, v21
	v_cvt_pk_bf16_f32 v19, v22, v23
	global_store_dwordx4 v1, v[16:19], s[4:5]
	v_mul_f32_e32 v27, v27, v160
	v_mul_f32_e32 v27, v91, v27
	v_mul_f32_e32 v26, v26, v160
	v_mul_f32_e32 v26, v90, v26
	v_mul_f32_e32 v25, v25, v160
	v_mul_f32_e32 v25, v89, v25
	v_mul_f32_e32 v24, v24, v160
	v_mul_f32_e32 v24, v88, v24
	v_add_f32_e32 v11, 1.0, v107
	v_fma_f32 v27, v11, v27, v123
	v_add_f32_e32 v10, 1.0, v106
	v_fma_f32 v26, v10, v26, v122
	v_add_f32_e32 v9, 1.0, v105
	v_fma_f32 v25, v9, v25, v121
	v_add_f32_e32 v8, 1.0, v104
	v_fma_f32 v24, v8, v24, v120
	v_mul_f32_e32 v31, v31, v160
	v_mul_f32_e32 v31, v95, v31
	v_mul_f32_e32 v30, v30, v160
	v_mul_f32_e32 v30, v94, v30
	v_mul_f32_e32 v29, v29, v160
	v_mul_f32_e32 v29, v93, v29
	v_mul_f32_e32 v28, v28, v160
	v_mul_f32_e32 v28, v92, v28
	v_add_f32_e32 v11, 1.0, v111
	v_fma_f32 v31, v11, v31, v127
	v_add_f32_e32 v10, 1.0, v110
	v_fma_f32 v30, v10, v30, v126
	v_add_f32_e32 v9, 1.0, v109
	v_fma_f32 v29, v9, v29, v125
	v_add_f32_e32 v8, 1.0, v108
	v_fma_f32 v28, v8, v28, v124
	v_cvt_pk_bf16_f32 v24, v24, v25
	v_cvt_pk_bf16_f32 v25, v26, v27
	v_cvt_pk_bf16_f32 v26, v28, v29
	v_cvt_pk_bf16_f32 v27, v30, v31
	global_store_dwordx4 v1, v[24:27], s[4:5] offset:1024
	s_sub_i32 s7, s10, 0x1000
	s_lshr_b32 s7, s7, 11
	s_add_i32 s7, s7, 1
	s_cmpk_lt_i32 s10, 0x1000
	s_cselect_b32 s7, 0, s7
	s_mulk_i32 s7, 0x6000
	s_add_i32 s7, s7, 0x3000
	s_add_u32 s4, s14, s7
	s_addc_u32 s5, s15, 0
	global_load_dwordx4 v[112:115], v0, s[4:5]
	global_load_dwordx4 v[116:119], v0, s[4:5] offset:16
	global_load_dwordx4 v[120:123], v0, s[4:5] offset:2048
	global_load_dwordx4 v[124:127], v0, s[4:5] offset:2064
	s_add_u32 s4, s4, 0x1000
	s_addc_u32 s5, s5, 0
	global_load_dwordx4 v[96:99], v0, s[4:5]
	global_load_dwordx4 v[100:103], v0, s[4:5] offset:16
	global_load_dwordx4 v[104:107], v0, s[4:5] offset:2048
	global_load_dwordx4 v[108:111], v0, s[4:5] offset:2064
	s_waitcnt vmcnt(10)
	s_lshl_b32 s7, s9, 11
	s_add_u32 s4, s34, s7
	s_addc_u32 s5, s35, 0
	s_add_u32 s4, s4, 0x8900000
	s_addc_u32 s5, s5, 0
	v_mul_f32_e32 v35, v35, v161
	v_mul_f32_e32 v35, v83, v35
	v_mul_f32_e32 v34, v34, v161
	v_mul_f32_e32 v34, v82, v34
	v_mul_f32_e32 v33, v33, v161
	v_mul_f32_e32 v33, v81, v33
	v_mul_f32_e32 v32, v32, v161
	v_mul_f32_e32 v32, v80, v32
	v_add_f32_e32 v11, 1.0, v131
	v_fma_f32 v35, v11, v35, v147
	v_add_f32_e32 v10, 1.0, v130
	v_fma_f32 v34, v10, v34, v146
	v_add_f32_e32 v9, 1.0, v129
	v_fma_f32 v33, v9, v33, v145
	v_add_f32_e32 v8, 1.0, v128
	v_fma_f32 v32, v8, v32, v144
	v_mul_f32_e32 v39, v39, v161
	v_mul_f32_e32 v39, v87, v39
	v_mul_f32_e32 v38, v38, v161
	v_mul_f32_e32 v38, v86, v38
	v_mul_f32_e32 v37, v37, v161
	v_mul_f32_e32 v37, v85, v37
	v_mul_f32_e32 v36, v36, v161
	v_mul_f32_e32 v36, v84, v36
	v_add_f32_e32 v11, 1.0, v135
	v_fma_f32 v39, v11, v39, v151
	v_add_f32_e32 v10, 1.0, v134
	v_fma_f32 v38, v10, v38, v150
	v_add_f32_e32 v9, 1.0, v133
	v_fma_f32 v37, v9, v37, v149
	v_add_f32_e32 v8, 1.0, v132
	v_fma_f32 v36, v8, v36, v148
	v_cvt_pk_bf16_f32 v32, v32, v33
	v_cvt_pk_bf16_f32 v33, v34, v35
	v_cvt_pk_bf16_f32 v34, v36, v37
	v_cvt_pk_bf16_f32 v35, v38, v39
	global_store_dwordx4 v1, v[32:35], s[4:5]
	v_mul_f32_e32 v43, v43, v161
	v_mul_f32_e32 v43, v91, v43
	v_mul_f32_e32 v42, v42, v161
	v_mul_f32_e32 v42, v90, v42
	v_mul_f32_e32 v41, v41, v161
	v_mul_f32_e32 v41, v89, v41
	v_mul_f32_e32 v40, v40, v161
	v_mul_f32_e32 v40, v88, v40
	v_add_f32_e32 v11, 1.0, v139
	v_fma_f32 v43, v11, v43, v155
	v_add_f32_e32 v10, 1.0, v138
	v_fma_f32 v42, v10, v42, v154
	v_add_f32_e32 v9, 1.0, v137
	v_fma_f32 v41, v9, v41, v153
	v_add_f32_e32 v8, 1.0, v136
	v_fma_f32 v40, v8, v40, v152
	v_mul_f32_e32 v47, v47, v161
	v_mul_f32_e32 v47, v95, v47
	v_mul_f32_e32 v46, v46, v161
	v_mul_f32_e32 v46, v94, v46
	v_mul_f32_e32 v45, v45, v161
	v_mul_f32_e32 v45, v93, v45
	v_mul_f32_e32 v44, v44, v161
	v_mul_f32_e32 v44, v92, v44
	v_add_f32_e32 v11, 1.0, v143
	v_fma_f32 v47, v11, v47, v159
	v_add_f32_e32 v10, 1.0, v142
	v_fma_f32 v46, v10, v46, v158
	v_add_f32_e32 v9, 1.0, v141
	v_fma_f32 v45, v9, v45, v157
	v_add_f32_e32 v8, 1.0, v140
	v_fma_f32 v44, v8, v44, v156
	v_cvt_pk_bf16_f32 v40, v40, v41
	v_cvt_pk_bf16_f32 v41, v42, v43
	v_cvt_pk_bf16_f32 v42, v44, v45
	v_cvt_pk_bf16_f32 v43, v46, v47
	global_store_dwordx4 v1, v[40:43], s[4:5] offset:1024
	s_sub_i32 s7, s11, 0x1000
	s_lshr_b32 s7, s7, 11
	s_add_i32 s7, s7, 1
	s_cmpk_lt_i32 s11, 0x1000
	s_cselect_b32 s7, 0, s7
	s_mulk_i32 s7, 0x6000
	s_add_i32 s7, s7, 0x3000
	s_add_u32 s4, s14, s7
	s_addc_u32 s5, s15, 0
	global_load_dwordx4 v[144:147], v0, s[4:5]
	global_load_dwordx4 v[148:151], v0, s[4:5] offset:16
	global_load_dwordx4 v[152:155], v0, s[4:5] offset:2048
	global_load_dwordx4 v[156:159], v0, s[4:5] offset:2064
	s_add_u32 s4, s4, 0x1000
	s_addc_u32 s5, s5, 0
	global_load_dwordx4 v[128:131], v0, s[4:5]
	global_load_dwordx4 v[132:135], v0, s[4:5] offset:16
	global_load_dwordx4 v[136:139], v0, s[4:5] offset:2048
	global_load_dwordx4 v[140:143], v0, s[4:5] offset:2064
	s_waitcnt vmcnt(10)
	s_lshl_b32 s7, s10, 11
	s_add_u32 s4, s34, s7
	s_addc_u32 s5, s35, 0
	s_add_u32 s4, s4, 0x8900000
	s_addc_u32 s5, s5, 0
	v_mul_f32_e32 v51, v51, v162
	v_mul_f32_e32 v51, v83, v51
	v_mul_f32_e32 v50, v50, v162
	v_mul_f32_e32 v50, v82, v50
	v_mul_f32_e32 v49, v49, v162
	v_mul_f32_e32 v49, v81, v49
	v_mul_f32_e32 v48, v48, v162
	v_mul_f32_e32 v48, v80, v48
	v_add_f32_e32 v11, 1.0, v99
	v_fma_f32 v51, v11, v51, v115
	v_add_f32_e32 v10, 1.0, v98
	v_fma_f32 v50, v10, v50, v114
	v_add_f32_e32 v9, 1.0, v97
	v_fma_f32 v49, v9, v49, v113
	v_add_f32_e32 v8, 1.0, v96
	v_fma_f32 v48, v8, v48, v112
	v_mul_f32_e32 v55, v55, v162
	v_mul_f32_e32 v55, v87, v55
	v_mul_f32_e32 v54, v54, v162
	v_mul_f32_e32 v54, v86, v54
	v_mul_f32_e32 v53, v53, v162
	v_mul_f32_e32 v53, v85, v53
	v_mul_f32_e32 v52, v52, v162
	v_mul_f32_e32 v52, v84, v52
	v_add_f32_e32 v11, 1.0, v103
	v_fma_f32 v55, v11, v55, v119
	v_add_f32_e32 v10, 1.0, v102
	v_fma_f32 v54, v10, v54, v118
	v_add_f32_e32 v9, 1.0, v101
	v_fma_f32 v53, v9, v53, v117
	v_add_f32_e32 v8, 1.0, v100
	v_fma_f32 v52, v8, v52, v116
	v_cvt_pk_bf16_f32 v48, v48, v49
	v_cvt_pk_bf16_f32 v49, v50, v51
	v_cvt_pk_bf16_f32 v50, v52, v53
	v_cvt_pk_bf16_f32 v51, v54, v55
	global_store_dwordx4 v1, v[48:51], s[4:5]
	v_mul_f32_e32 v59, v59, v162
	v_mul_f32_e32 v59, v91, v59
	v_mul_f32_e32 v58, v58, v162
	v_mul_f32_e32 v58, v90, v58
	v_mul_f32_e32 v57, v57, v162
	v_mul_f32_e32 v57, v89, v57
	v_mul_f32_e32 v56, v56, v162
	v_mul_f32_e32 v56, v88, v56
	v_add_f32_e32 v11, 1.0, v107
	v_fma_f32 v59, v11, v59, v123
	v_add_f32_e32 v10, 1.0, v106
	v_fma_f32 v58, v10, v58, v122
	v_add_f32_e32 v9, 1.0, v105
	v_fma_f32 v57, v9, v57, v121
	v_add_f32_e32 v8, 1.0, v104
	v_fma_f32 v56, v8, v56, v120
	v_mul_f32_e32 v63, v63, v162
	v_mul_f32_e32 v63, v95, v63
	v_mul_f32_e32 v62, v62, v162
	v_mul_f32_e32 v62, v94, v62
	v_mul_f32_e32 v61, v61, v162
	v_mul_f32_e32 v61, v93, v61
	v_mul_f32_e32 v60, v60, v162
	v_mul_f32_e32 v60, v92, v60
	v_add_f32_e32 v11, 1.0, v111
	v_fma_f32 v63, v11, v63, v127
	v_add_f32_e32 v10, 1.0, v110
	v_fma_f32 v62, v10, v62, v126
	v_add_f32_e32 v9, 1.0, v109
	v_fma_f32 v61, v9, v61, v125
	v_add_f32_e32 v8, 1.0, v108
	v_fma_f32 v60, v8, v60, v124
	v_cvt_pk_bf16_f32 v56, v56, v57
	v_cvt_pk_bf16_f32 v57, v58, v59
	v_cvt_pk_bf16_f32 v58, v60, v61
	v_cvt_pk_bf16_f32 v59, v62, v63
	global_store_dwordx4 v1, v[56:59], s[4:5] offset:1024
	s_waitcnt vmcnt(2)
	s_lshl_b32 s7, s11, 11
	s_add_u32 s4, s34, s7
	s_addc_u32 s5, s35, 0
	s_add_u32 s4, s4, 0x8900000
	s_addc_u32 s5, s5, 0
	v_mul_f32_e32 v67, v67, v163
	v_mul_f32_e32 v67, v83, v67
	v_mul_f32_e32 v66, v66, v163
	v_mul_f32_e32 v66, v82, v66
	v_mul_f32_e32 v65, v65, v163
	v_mul_f32_e32 v65, v81, v65
	v_mul_f32_e32 v64, v64, v163
	v_mul_f32_e32 v64, v80, v64
	v_add_f32_e32 v11, 1.0, v131
	v_fma_f32 v67, v11, v67, v147
	v_add_f32_e32 v10, 1.0, v130
	v_fma_f32 v66, v10, v66, v146
	v_add_f32_e32 v9, 1.0, v129
	v_fma_f32 v65, v9, v65, v145
	v_add_f32_e32 v8, 1.0, v128
	v_fma_f32 v64, v8, v64, v144
	v_mul_f32_e32 v71, v71, v163
	v_mul_f32_e32 v71, v87, v71
	v_mul_f32_e32 v70, v70, v163
	v_mul_f32_e32 v70, v86, v70
	v_mul_f32_e32 v69, v69, v163
	v_mul_f32_e32 v69, v85, v69
	v_mul_f32_e32 v68, v68, v163
	v_mul_f32_e32 v68, v84, v68
	v_add_f32_e32 v11, 1.0, v135
	v_fma_f32 v71, v11, v71, v151
	v_add_f32_e32 v10, 1.0, v134
	v_fma_f32 v70, v10, v70, v150
	v_add_f32_e32 v9, 1.0, v133
	v_fma_f32 v69, v9, v69, v149
	v_add_f32_e32 v8, 1.0, v132
	v_fma_f32 v68, v8, v68, v148
	v_cvt_pk_bf16_f32 v64, v64, v65
	v_cvt_pk_bf16_f32 v65, v66, v67
	v_cvt_pk_bf16_f32 v66, v68, v69
	v_cvt_pk_bf16_f32 v67, v70, v71
	global_store_dwordx4 v1, v[64:67], s[4:5]
	v_mul_f32_e32 v75, v75, v163
	v_mul_f32_e32 v75, v91, v75
	v_mul_f32_e32 v74, v74, v163
	v_mul_f32_e32 v74, v90, v74
	v_mul_f32_e32 v73, v73, v163
	v_mul_f32_e32 v73, v89, v73
	v_mul_f32_e32 v72, v72, v163
	v_mul_f32_e32 v72, v88, v72
	v_add_f32_e32 v11, 1.0, v139
	v_fma_f32 v75, v11, v75, v155
	v_add_f32_e32 v10, 1.0, v138
	v_fma_f32 v74, v10, v74, v154
	v_add_f32_e32 v9, 1.0, v137
	v_fma_f32 v73, v9, v73, v153
	v_add_f32_e32 v8, 1.0, v136
	v_fma_f32 v72, v8, v72, v152
	v_mul_f32_e32 v79, v79, v163
	v_mul_f32_e32 v79, v95, v79
	v_mul_f32_e32 v78, v78, v163
	v_mul_f32_e32 v78, v94, v78
	v_mul_f32_e32 v77, v77, v163
	v_mul_f32_e32 v77, v93, v77
	v_mul_f32_e32 v76, v76, v163
	v_mul_f32_e32 v76, v92, v76
	v_add_f32_e32 v11, 1.0, v143
	v_fma_f32 v79, v11, v79, v159
	v_add_f32_e32 v10, 1.0, v142
	v_fma_f32 v78, v10, v78, v158
	v_add_f32_e32 v9, 1.0, v141
	v_fma_f32 v77, v9, v77, v157
	v_add_f32_e32 v8, 1.0, v140
	v_fma_f32 v76, v8, v76, v156
	v_cvt_pk_bf16_f32 v72, v72, v73
	v_cvt_pk_bf16_f32 v73, v74, v75
	v_cvt_pk_bf16_f32 v74, v76, v77
	v_cvt_pk_bf16_f32 v75, v78, v79
	global_store_dwordx4 v1, v[72:75], s[4:5] offset:1024
	s_lshl_b32 s7, s6, 2
	s_add_i32 s3, s3, s7
	s_cmpk_lt_i32 s3, 0x2000
	s_cbranch_scc1 .Lnorm2_loop
